# NSA: per-segment s_setprio raises neutralised (all segments at priority 0)
# speedup vs baseline: 1.0017x; 1.0017x over previous
; #define LAS __attribute__((address_space(3)))
; #define NSA_PRIO_ON(c) do { if ((c).hiw) __builtin_amdgcn_s_setprio(3); else __builtin_amdgcn_s_setprio(1); } while (0)
; template <int BR> __device__ __forceinline__ void nsa_s_tile(LAS unsigned char* L, int slot, const NsaBr& c, const bf16x8 (&qr)[4], f32x16 (&sa)[2]) {
;     NSA_PRIO_ON(c);
.LBB0_1758:
	s_cmp_gt_i32 s5, 3
	s_cselect_b64 s[36:37], -1, 0
	s_mov_b64 s[0:1], -1
	s_and_b64 vcc, exec, s[36:37]
	s_cbranch_vccz .LBB0_1760
	s_setprio 0
	s_mov_b64 s[0:1], 0
.LBB0_1760:
	s_andn2_b64 vcc, exec, s[0:1]
	s_cbranch_vccnz .LBB0_1762
	s_setprio 0

; #define LAS __attribute__((address_space(3)))
; #define NSA_PRIO_ON(c) do { if ((c).hiw) __builtin_amdgcn_s_setprio(3); else __builtin_amdgcn_s_setprio(1); } while (0)
; template <int BR> __device__ __forceinline__ void nsa_s_tile(LAS unsigned char* L, int slot, const NsaBr& c, const bf16x8 (&qr)[4], f32x16 (&sa)[2]) {
;     NSA_PRIO_ON(c);
; template <int BR> __device__ __forceinline__ void nsa_step(LAS unsigned char* L, const NsaBr& c, const bf16x8 (&qr)[4], int jj, int nblk, int s_cur, int s_nxt, int s_wr, ...
;     ...
;     if (jj + 2 < nblk) { nsa_kv_write(L, s_wr, c, kreg, vreg); if (jj + 3 < nblk) nsa_kv_load(c, c.jlo + jj + 3, kreg, vreg); }
;     if (jj + 1 < nblk) nsa_s_tile<BR>(L, s_nxt, c, qr, nxt);
.LBB0_1766:
	s_cmp_lt_u32 s31, s8
	s_cselect_b64 s[26:27], -1, 0
	s_cmp_ge_u32 s31, s8
	s_cbranch_scc1 .LBB0_1792
	s_mov_b64 s[4:5], -1
	s_and_b64 vcc, exec, s[36:37]
	s_cbranch_vccz .LBB0_1769
	s_setprio 0
	s_mov_b64 s[4:5], 0
.LBB0_1769:
	s_andn2_b64 vcc, exec, s[4:5]
	s_cbranch_vccnz .LBB0_1771
	s_setprio 0

; #define NSA_PRIO_ON(c) do { if ((c).hiw) __builtin_amdgcn_s_setprio(3); else __builtin_amdgcn_s_setprio(1); } while (0)
; template <int BR> __device__ __forceinline__ void nsa_softmax_pv(LAS unsigned char* L, int slot, const NsaBr& c, int j, f32x16 (&sa)[2], f32x16 (&oacc)[2], float& mrun, float& lrun) {
;     ...
;     const float msub = (BR == 1 && !mine) ? 1e30f : mrun;
;     f32x2 ps2 = {0.f, 0.f}; float nmsub = -msub; asm volatile("" : "+v"(nmsub)); const f32x2 nm2 = {nmsub, nmsub};
; #pragma unroll
;     for (int kt = 0; kt < 2; ++kt) {
; #pragma unroll
;         for (int i = 0; i < 16; i += 2) { const f32x2 x = (f32x2){sa[kt][i], sa[kt][i + 1]} + nm2; sa[kt][i] = __builtin_amdgcn_exp2f(x.x); sa[kt][i + 1] = __builtin_amdgcn_exp2f(x.y); }
; #pragma unroll
;         for (int i = 0; i < 16; i += 2) ps2 += (f32x2){sa[kt][i], sa[kt][i + 1]};
;     }
;     const float psum = ps2.x + ps2.y;
;     lrun += psum;
;     NSA_PRIO_ON(c);
.LBB0_1776:
	v_cndmask_b32_e64 v202, -v218, v234, s[94:95]
	s_mov_b64 s[4:5], -1
	s_and_b64 vcc, exec, s[36:37]
	s_cbranch_vccz .LBB0_1778
	s_setprio 0
	s_mov_b64 s[4:5], 0

; #define LAS __attribute__((address_space(3)))
; #define NSA_PRIO_ON(c) do { if ((c).hiw) __builtin_amdgcn_s_setprio(3); else __builtin_amdgcn_s_setprio(1); } while (0)
; template <int BR> __device__ __forceinline__ void nsa_s_tile(LAS unsigned char* L, int slot, const NsaBr& c, const bf16x8 (&qr)[4], f32x16 (&sa)[2]) {
;     NSA_PRIO_ON(c);
; template <int BR> __device__ __forceinline__ void nsa_step(LAS unsigned char* L, const NsaBr& c, const bf16x8 (&qr)[4], int jj, int nblk, int s_cur, int s_nxt, int s_wr, ...
;     ...
;     if (jj + 2 < nblk) { nsa_kv_write(L, s_wr, c, kreg, vreg); if (jj + 3 < nblk) nsa_kv_load(c, c.jlo + jj + 3, kreg, vreg); }
;     if (jj + 1 < nblk) nsa_s_tile<BR>(L, s_nxt, c, qr, nxt);
.LBB0_1784:
	s_andn2_b64 vcc, exec, s[96:97]
	s_cbranch_vccnz .LBB0_1790
	s_mov_b64 s[4:5], -1
	s_and_b64 vcc, exec, s[36:37]
	s_cbranch_vccz .LBB0_1787
	s_setprio 0
	s_mov_b64 s[4:5], 0

; #define NSA_PRIO_ON(c) do { if ((c).hiw) __builtin_amdgcn_s_setprio(3); else __builtin_amdgcn_s_setprio(1); } while (0)
; template <int BR> __device__ __forceinline__ void nsa_softmax_pv(LAS unsigned char* L, int slot, const NsaBr& c, int j, f32x16 (&sa)[2], f32x16 (&oacc)[2], float& mrun, float& lrun) {
;     ...
;     const float msub = (BR == 1 && !mine) ? 1e30f : mrun;
;     f32x2 ps2 = {0.f, 0.f}; float nmsub = -msub; asm volatile("" : "+v"(nmsub)); const f32x2 nm2 = {nmsub, nmsub};
; #pragma unroll
;     for (int kt = 0; kt < 2; ++kt) {
; #pragma unroll
;         for (int i = 0; i < 16; i += 2) { const f32x2 x = (f32x2){sa[kt][i], sa[kt][i + 1]} + nm2; sa[kt][i] = __builtin_amdgcn_exp2f(x.x); sa[kt][i + 1] = __builtin_amdgcn_exp2f(x.y); }
; #pragma unroll
;         for (int i = 0; i < 16; i += 2) ps2 += (f32x2){sa[kt][i], sa[kt][i + 1]};
;     }
;     const float psum = ps2.x + ps2.y;
;     lrun += psum;
;     NSA_PRIO_ON(c);
.LBB0_1798:
	v_cndmask_b32_e64 v202, v202, v234, s[94:95]
	s_mov_b64 s[4:5], -1
	s_and_b64 vcc, exec, s[36:37]
	s_cbranch_vccz .LBB0_1800
	s_setprio 0
	s_mov_b64 s[4:5], 0

; #define LAS __attribute__((address_space(3)))
; #define LDS_BARRIER() do { asm volatile("s_waitcnt lgkmcnt(0)" ::: "memory"); __builtin_amdgcn_s_barrier(); asm volatile("" ::: "memory"); } while (0)
; #define NSA_PRIO_ON(c) do { if ((c).hiw) __builtin_amdgcn_s_setprio(3); else __builtin_amdgcn_s_setprio(1); } while (0)
; template <int BR> __device__ __forceinline__ void nsa_s_tile(LAS unsigned char* L, int slot, const NsaBr& c, const bf16x8 (&qr)[4], f32x16 (&sa)[2]) {
;     NSA_PRIO_ON(c);
; template <int BR>
; __device__ __forceinline__ void nsa_branch(const Frame& F, int plane, int qt, int t, int r, int h, unsigned selmask, const bf16x8 (&qr)[4], float gate) {
;     ...
;     LDS_BARRIER();
;     if (nblk > 1) { nsa_kv_write(L, NL_SLOT, c, kreg, vreg); if (nblk > 2) nsa_kv_load(c, c.jlo + 2, kreg, vreg); }
;     nsa_s_tile<BR>(L, 0, c, qr, sa);
.LBB0_1810:
	s_mov_b64 s[4:5], -1
	s_and_b64 vcc, exec, s[36:37]
	s_cbranch_vccz .LBB0_1812
	s_setprio 0
	s_mov_b64 s[4:5], 0

; #define LAS __attribute__((address_space(3)))
; #define NSA_PRIO_ON(c) do { if ((c).hiw) __builtin_amdgcn_s_setprio(3); else __builtin_amdgcn_s_setprio(1); } while (0)
; template <int BR> __device__ __forceinline__ void nsa_s_tile(LAS unsigned char* L, int slot, const NsaBr& c, const bf16x8 (&qr)[4], f32x16 (&sa)[2]) {
;     NSA_PRIO_ON(c);
; template <int BR> __device__ __forceinline__ void nsa_step(LAS unsigned char* L, const NsaBr& c, const bf16x8 (&qr)[4], int jj, int nblk, int s_cur, int s_nxt, int s_wr, ...
;     ...
;     if (jj + 2 < nblk) { nsa_kv_write(L, s_wr, c, kreg, vreg); if (jj + 3 < nblk) nsa_kv_load(c, c.jlo + jj + 3, kreg, vreg); }
;     if (jj + 1 < nblk) nsa_s_tile<BR>(L, s_nxt, c, qr, nxt);
.LBB0_1818:
	s_cmp_lt_u32 s3, s9
	s_cselect_b64 s[46:47], -1, 0
	s_cmp_ge_u32 s3, s9
	s_cbranch_scc1 .LBB0_1824
	s_mov_b64 s[0:1], -1
	s_and_b64 vcc, exec, s[36:37]
	s_cbranch_vccz .LBB0_1821
	s_setprio 0
	s_mov_b64 s[0:1], 0

; #define NSA_PRIO_ON(c) do { if ((c).hiw) __builtin_amdgcn_s_setprio(3); else __builtin_amdgcn_s_setprio(1); } while (0)
; template <int BR> __device__ __forceinline__ void nsa_softmax_pv(LAS unsigned char* L, int slot, const NsaBr& c, int j, f32x16 (&sa)[2], f32x16 (&oacc)[2], float& mrun, float& lrun) {
;     ...
;     const float msub = (BR == 1 && !mine) ? 1e30f : mrun;
;     f32x2 ps2 = {0.f, 0.f}; float nmsub = -msub; asm volatile("" : "+v"(nmsub)); const f32x2 nm2 = {nmsub, nmsub};
; #pragma unroll
;     for (int kt = 0; kt < 2; ++kt) {
; #pragma unroll
;         for (int i = 0; i < 16; i += 2) { const f32x2 x = (f32x2){sa[kt][i], sa[kt][i + 1]} + nm2; sa[kt][i] = __builtin_amdgcn_exp2f(x.x); sa[kt][i + 1] = __builtin_amdgcn_exp2f(x.y); }
; #pragma unroll
;         for (int i = 0; i < 16; i += 2) ps2 += (f32x2){sa[kt][i], sa[kt][i + 1]};
;     }
;     const float psum = ps2.x + ps2.y;
;     lrun += psum;
;     NSA_PRIO_ON(c);
.LBB0_1830:
	v_xor_b32_e32 v122, 0x80000000, v174
	v_mov_b32_e32 v138, v122
	s_mov_b64 s[0:1], -1
	s_and_b64 vcc, exec, s[36:37]
	s_cbranch_vccz .LBB0_1832
	s_setprio 0
	s_mov_b64 s[0:1], 0

; #define LAS __attribute__((address_space(3)))
; #define NSA_PRIO_ON(c) do { if ((c).hiw) __builtin_amdgcn_s_setprio(3); else __builtin_amdgcn_s_setprio(1); } while (0)
; template <int BR> __device__ __forceinline__ void nsa_s_tile(LAS unsigned char* L, int slot, const NsaBr& c, const bf16x8 (&qr)[4], f32x16 (&sa)[2]) {
;     NSA_PRIO_ON(c);
; template <int BR> __device__ __forceinline__ void nsa_step(LAS unsigned char* L, const NsaBr& c, const bf16x8 (&qr)[4], int jj, int nblk, int s_cur, int s_nxt, int s_wr, ...
;     ...
;     if (jj + 2 < nblk) { nsa_kv_write(L, s_wr, c, kreg, vreg); if (jj + 3 < nblk) nsa_kv_load(c, c.jlo + jj + 3, kreg, vreg); }
;     if (jj + 1 < nblk) nsa_s_tile<BR>(L, s_nxt, c, qr, nxt);
.LBB0_1838:
	s_cmp_gt_i32 s3, s11
	s_cbranch_scc1 .LBB0_1855
	s_mov_b64 s[0:1], -1
	s_and_b64 vcc, exec, s[36:37]
	s_cbranch_vccz .LBB0_1841
	s_setprio 0
	s_mov_b64 s[0:1], 0

; #define NSA_PRIO_ON(c) do { if ((c).hiw) __builtin_amdgcn_s_setprio(3); else __builtin_amdgcn_s_setprio(1); } while (0)
; template <int BR> __device__ __forceinline__ void nsa_softmax_pv(LAS unsigned char* L, int slot, const NsaBr& c, int j, f32x16 (&sa)[2], f32x16 (&oacc)[2], float& mrun, float& lrun) {
;     ...
;     const float msub = (BR == 1 && !mine) ? 1e30f : mrun;
;     f32x2 ps2 = {0.f, 0.f}; float nmsub = -msub; asm volatile("" : "+v"(nmsub)); const f32x2 nm2 = {nmsub, nmsub};
; #pragma unroll
;     for (int kt = 0; kt < 2; ++kt) {
; #pragma unroll
;         for (int i = 0; i < 16; i += 2) { const f32x2 x = (f32x2){sa[kt][i], sa[kt][i + 1]} + nm2; sa[kt][i] = __builtin_amdgcn_exp2f(x.x); sa[kt][i + 1] = __builtin_amdgcn_exp2f(x.y); }
; #pragma unroll
;         for (int i = 0; i < 16; i += 2) ps2 += (f32x2){sa[kt][i], sa[kt][i + 1]};
;     }
;     const float psum = ps2.x + ps2.y;
;     lrun += psum;
;     NSA_PRIO_ON(c);
.LBB0_1848:
	s_mov_b64 s[0:1], -1
	s_and_b64 vcc, exec, s[36:37]
	s_cbranch_vccz .LBB0_1850
	s_setprio 0
	s_mov_b64 s[0:1], 0
